# non-deferred tile boundary: next row panel's row sums requested at the start of the standalone tail (ahead of its stores), counted wait in the header
# speedup vs baseline: 1.0054x; 1.0054x over previous
; __device__ __forceinline__ void load_rstd(float (&rsv)[2][4], const ssq_t* ssq, int row0) {
;     ssq_t t[2][4];
; #pragma unroll
;     for (int ai = 0; ai < 2; ++ai)
; #pragma unroll
;         for (int m = 0; m < 4; ++m) t[ai][m] = ssq[row0 + ai * HALF + m * 16];
; #pragma unroll
;     for (int ai = 0; ai < 2; ++ai)
; #pragma unroll
;         for (int m = 0; m < 4; ++m) rsv[ai][m] = __builtin_amdgcn_rsqf((float)t[ai][m] * (SSQ_INV / 1024.0f) + 1e-6f);
; }
.LBB0_306:
	s_andn2_b64 vcc, exec, s[36:37]
	s_cbranch_vccnz .LBB0_309
	v_lshl_add_u64 v[142:143], v[142:143], 0, s[92:93]
	v_lshl_add_u64 v[144:145], v[144:145], 0, s[80:81]
	s_mov_b32 s10, 0
	v_readfirstlane_b32 s98, v254
	s_cmp_eq_u32 s98, s64
	s_cbranch_scc1 .Lgu_rs_ok
	s_or_b32 s99, s64, 0x40000000
	s_cmp_eq_u32 s98, s99
	s_cbranch_scc1 .Lgu_rs_wait
	v_lshrrev_b32_e32 v194, 8, v170
	v_and_b32_e32 v195, 15, v170
	v_lshl_add_u32 v194, v194, 6, v195
	s_lshl_b32 s98, s64, 8
	v_add_u32_e32 v194, s98, v194
	v_lshlrev_b32_e32 v192, 3, v194
	v_mov_b32_e32 v193, 0
	v_lshl_add_u64 v[192:193], v[192:193], 0, s[26:27]
	global_load_dwordx2 v[176:177], v[192:193], off
	global_load_dwordx2 v[178:179], v[192:193], off offset:128
	global_load_dwordx2 v[180:181], v[192:193], off offset:256
	global_load_dwordx2 v[182:183], v[192:193], off offset:384
	global_load_dwordx2 v[184:185], v[192:193], off offset:1024
	global_load_dwordx2 v[186:187], v[192:193], off offset:1152
	global_load_dwordx2 v[188:189], v[192:193], off offset:1280
	global_load_dwordx2 v[190:191], v[192:193], off offset:1408
	s_waitcnt vmcnt(0)
	s_branch .Lgu_rs_cvt
.Lgu_rs_wait:
	s_waitcnt vmcnt(4)
.Lgu_rs_cvt:
	v_ffbh_u32_e32 v194, v177
	v_min_u32_e32 v194, 32, v194
	v_lshlrev_b64 v[176:177], v194, v[176:177]
	v_min_u32_e32 v176, 1, v176
	v_or_b32_e32 v176, v177, v176
	v_cvt_f32_u32_e32 v176, v176
	v_sub_u32_e32 v194, 32, v194
	v_ldexp_f32 v176, v176, v194
	v_fmamk_f32 v176, v176, 0x30800000, v223
	v_rsq_f32_e32 v176, v176
	v_ffbh_u32_e32 v194, v179
	v_min_u32_e32 v194, 32, v194
	v_lshlrev_b64 v[178:179], v194, v[178:179]
	v_min_u32_e32 v178, 1, v178
	v_or_b32_e32 v178, v179, v178
	v_cvt_f32_u32_e32 v178, v178
	v_sub_u32_e32 v194, 32, v194
	v_ldexp_f32 v178, v178, v194
	v_fmamk_f32 v178, v178, 0x30800000, v223
	v_rsq_f32_e32 v178, v178
	v_ffbh_u32_e32 v194, v181
	v_min_u32_e32 v194, 32, v194
	v_lshlrev_b64 v[180:181], v194, v[180:181]
	v_min_u32_e32 v180, 1, v180
	v_or_b32_e32 v180, v181, v180
	v_cvt_f32_u32_e32 v180, v180
	v_sub_u32_e32 v194, 32, v194
	v_ldexp_f32 v180, v180, v194
	v_fmamk_f32 v180, v180, 0x30800000, v223
	v_rsq_f32_e32 v180, v180
	v_ffbh_u32_e32 v194, v183
	v_min_u32_e32 v194, 32, v194
	v_lshlrev_b64 v[182:183], v194, v[182:183]
	v_min_u32_e32 v182, 1, v182
	v_or_b32_e32 v182, v183, v182
	v_cvt_f32_u32_e32 v182, v182
	v_sub_u32_e32 v194, 32, v194
	v_ldexp_f32 v182, v182, v194
	v_fmamk_f32 v182, v182, 0x30800000, v223
	v_rsq_f32_e32 v182, v182
	v_ffbh_u32_e32 v194, v185
	v_min_u32_e32 v194, 32, v194
	v_lshlrev_b64 v[184:185], v194, v[184:185]
	v_min_u32_e32 v184, 1, v184
	v_or_b32_e32 v184, v185, v184
	v_cvt_f32_u32_e32 v184, v184
	v_sub_u32_e32 v194, 32, v194
	v_ldexp_f32 v184, v184, v194
	v_fmamk_f32 v184, v184, 0x30800000, v223
	v_rsq_f32_e32 v184, v184
	v_ffbh_u32_e32 v194, v187
	v_min_u32_e32 v194, 32, v194
	v_lshlrev_b64 v[186:187], v194, v[186:187]
	v_min_u32_e32 v186, 1, v186
	v_or_b32_e32 v186, v187, v186
	v_cvt_f32_u32_e32 v186, v186
	v_sub_u32_e32 v194, 32, v194
	v_ldexp_f32 v186, v186, v194
	v_fmamk_f32 v186, v186, 0x30800000, v223
	v_rsq_f32_e32 v186, v186
	v_ffbh_u32_e32 v194, v189
	v_min_u32_e32 v194, 32, v194
	v_lshlrev_b64 v[188:189], v194, v[188:189]
	v_min_u32_e32 v188, 1, v188
	v_or_b32_e32 v188, v189, v188
	v_cvt_f32_u32_e32 v188, v188
	v_sub_u32_e32 v194, 32, v194
	v_ldexp_f32 v188, v188, v194
	v_fmamk_f32 v188, v188, 0x30800000, v223
	v_rsq_f32_e32 v188, v188
	v_ffbh_u32_e32 v194, v191
	v_min_u32_e32 v194, 32, v194
	v_lshlrev_b64 v[190:191], v194, v[190:191]
	v_min_u32_e32 v190, 1, v190
	v_or_b32_e32 v190, v191, v190
	v_cvt_f32_u32_e32 v190, v190
	v_sub_u32_e32 v194, 32, v194
	v_ldexp_f32 v190, v190, v194
	v_fmamk_f32 v190, v190, 0x30800000, v223
	v_rsq_f32_e32 v190, v190
	v_mov_b32_e32 v172, v176
	v_mov_b32_e32 v173, v178
	v_mov_b32_e32 v236, v180
	v_mov_b32_e32 v237, v182
	v_mov_b32_e32 v238, v184
	v_mov_b32_e32 v239, v186
	v_mov_b32_e32 v230, v188
	v_mov_b32_e32 v231, v190
	v_mov_b32_e32 v254, s64

; __device__ __forceinline__ unsigned cvt_pk_bf16(float lo, float hi) { unsigned r; asm volatile("v_cvt_pk_bf16_f32 %0, %1, %2" : "=v"(r) : "v"(lo), "v"(hi)); return r; }
; __device__ __forceinline__ float siluf_(float x) { return x * sigmoidf_(x); }
; __device__ __forceinline__ void load_rstd(float (&rsv)[2][4], const ssq_t* ssq, int row0) {
;     ssq_t t[2][4];
; #pragma unroll
;     for (int ai = 0; ai < 2; ++ai)
; #pragma unroll
;         for (int m = 0; m < 4; ++m) t[ai][m] = ssq[row0 + ai * HALF + m * 16];
;     __device__ __forceinline__ void operator()(const f32x4 (&acc)[2][2][4][2], const Unit& u, int wr, int wc, int fr, int fq) const {
;         const int row0 = u.pm * BM + wr * 64 + fr, col0 = u.pn * HALF + wc * 32 + 8 * fq;
;         float rsv[2][4]; load_rstd(rsv, ssq, row0);
; #pragma unroll
;         for (int ai = 0; ai < 2; ++ai)
; #pragma unroll
;             for (int m = 0; m < 4; ++m) { const int row = row0 + ai * HALF + m * 16; bf16_t* rowp = O + (size_t)row * ldc + col0; const float rs = rsv[ai][m];
;                 f32x4 v0, v1;
; #pragma unroll
;                 for (int j = 0; j < 4; ++j) { v0[j] = siluf_(acc[ai][0][m][0][j] * rs) * (acc[ai][1][m][0][j] * rs); v1[j] = siluf_(acc[ai][0][m][1][j] * rs) * (acc[ai][1][m][1][j] * rs); }
;                 u32x4 w; w.x = cvt_pk_bf16(v0[0], v0[1]); w.y = cvt_pk_bf16(v0[2], v0[3]); w.z = cvt_pk_bf16(v1[0], v1[1]); w.w = cvt_pk_bf16(v1[2], v1[3]);
;                 *(u32x4*)rowp = w; }
.LBB0_311:
	s_nop 15
	s_nop 15
	s_and_b64 vcc, exec, s[8:9]
	s_cbranch_vccnz .Lgu_nopf
	s_cmp_eq_u32 s62, s64
	s_cbranch_scc1 .Lgu_nopf
	v_lshrrev_b32_e32 v194, 8, v170
	v_and_b32_e32 v195, 15, v170
	v_lshl_add_u32 v194, v194, 6, v195
	s_lshl_b32 s98, s62, 8
	v_add_u32_e32 v194, s98, v194
	v_lshlrev_b32_e32 v192, 3, v194
	v_mov_b32_e32 v193, 0
	v_lshl_add_u64 v[192:193], v[192:193], 0, s[26:27]
	global_load_dwordx2 v[176:177], v[192:193], off
	global_load_dwordx2 v[178:179], v[192:193], off offset:128
	global_load_dwordx2 v[180:181], v[192:193], off offset:256
	global_load_dwordx2 v[182:183], v[192:193], off offset:384
	global_load_dwordx2 v[184:185], v[192:193], off offset:1024
	global_load_dwordx2 v[186:187], v[192:193], off offset:1152
	global_load_dwordx2 v[188:189], v[192:193], off offset:1280
	global_load_dwordx2 v[190:191], v[192:193], off offset:1408
	s_or_b32 s98, s62, 0x40000000
	v_mov_b32_e32 v254, s98
.Lgu_nopf:
	s_lshl_b32 s98, s28, 5
	s_mov_b32 s99, 0
	s_mov_b32 s100, 0xbfb8aa3b
	s_mov_b32 s101, 0xbfb8aa3b
	v_pk_mul_f32 v[56:57], v[56:57], v[238:239] op_sel_hi:[1,0]
	v_pk_mul_f32 v[58:59], v[58:59], v[238:239] op_sel_hi:[1,0]
	v_pk_mul_f32 v[60:61], v[60:61], v[238:239] op_sel_hi:[1,0]
	v_pk_mul_f32 v[62:63], v[62:63], v[238:239] op_sel_hi:[1,0]
	v_pk_mul_f32 v[224:225], v[56:57], s[100:101]
	v_pk_mul_f32 v[228:229], v[58:59], s[100:101]
	v_exp_f32_e32 v224, v224
	v_exp_f32_e32 v225, v225
	v_exp_f32_e32 v228, v228
	v_exp_f32_e32 v229, v229
	v_add_f32_e32 v224, 1.0, v224
	v_add_f32_e32 v225, 1.0, v225
	v_add_f32_e32 v228, 1.0, v228
	v_add_f32_e32 v229, 1.0, v229
	v_rcp_f32_e32 v224, v224
	v_rcp_f32_e32 v225, v225
	v_rcp_f32_e32 v228, v228
	v_rcp_f32_e32 v229, v229
	v_nop
	v_pk_mul_f32 v[56:57], v[56:57], v[224:225]
	v_pk_mul_f32 v[58:59], v[58:59], v[228:229]
	v_pk_mul_f32 v[56:57], v[56:57], v[60:61]
	v_pk_mul_f32 v[58:59], v[58:59], v[62:63]
	v_pk_mul_f32 v[48:49], v[48:49], v[238:239] op_sel_hi:[1,0]
	v_pk_mul_f32 v[50:51], v[50:51], v[238:239] op_sel_hi:[1,0]
	v_pk_mul_f32 v[52:53], v[52:53], v[238:239] op_sel_hi:[1,0]
	v_pk_mul_f32 v[54:55], v[54:55], v[238:239] op_sel_hi:[1,0]
	v_pk_mul_f32 v[224:225], v[48:49], s[100:101]
	v_pk_mul_f32 v[228:229], v[50:51], s[100:101]
	v_exp_f32_e32 v224, v224
	v_exp_f32_e32 v225, v225
	v_exp_f32_e32 v228, v228
	v_exp_f32_e32 v229, v229
	v_add_f32_e32 v224, 1.0, v224
	v_add_f32_e32 v225, 1.0, v225
	v_add_f32_e32 v228, 1.0, v228
	v_add_f32_e32 v229, 1.0, v229
	v_rcp_f32_e32 v224, v224
	v_rcp_f32_e32 v225, v225
	v_rcp_f32_e32 v228, v228
	v_rcp_f32_e32 v229, v229
	v_nop
	v_pk_mul_f32 v[48:49], v[48:49], v[224:225]
	v_pk_mul_f32 v[50:51], v[50:51], v[228:229]
	v_pk_mul_f32 v[48:49], v[48:49], v[52:53]
	v_pk_mul_f32 v[50:51], v[50:51], v[54:55]
	v_cvt_pk_bf16_f32 v56, v56, v57
	v_cvt_pk_bf16_f32 v57, v58, v59
	v_cvt_pk_bf16_f32 v58, v48, v49
	v_cvt_pk_bf16_f32 v59, v50, v51
	global_store_dwordx4 v[232:233], v[56:59], off
	v_lshl_add_u64 v[232:233], v[232:233], 0, s[98:99]
	v_pk_mul_f32 v[40:41], v[40:41], v[238:239] op_sel:[0,1]
	v_pk_mul_f32 v[42:43], v[42:43], v[238:239] op_sel:[0,1]
	v_pk_mul_f32 v[44:45], v[44:45], v[238:239] op_sel:[0,1]
	v_pk_mul_f32 v[46:47], v[46:47], v[238:239] op_sel:[0,1]
	v_pk_mul_f32 v[224:225], v[40:41], s[100:101]
	v_pk_mul_f32 v[228:229], v[42:43], s[100:101]
	v_exp_f32_e32 v224, v224
	v_exp_f32_e32 v225, v225
	v_exp_f32_e32 v228, v228
	v_exp_f32_e32 v229, v229
	v_add_f32_e32 v224, 1.0, v224
	v_add_f32_e32 v225, 1.0, v225
	v_add_f32_e32 v228, 1.0, v228
	v_add_f32_e32 v229, 1.0, v229
	v_rcp_f32_e32 v224, v224
	v_rcp_f32_e32 v225, v225
	v_rcp_f32_e32 v228, v228
	v_rcp_f32_e32 v229, v229
	v_nop
	v_pk_mul_f32 v[40:41], v[40:41], v[224:225]
	v_pk_mul_f32 v[42:43], v[42:43], v[228:229]
	v_pk_mul_f32 v[40:41], v[40:41], v[44:45]
	v_pk_mul_f32 v[42:43], v[42:43], v[46:47]
	v_pk_mul_f32 v[32:33], v[32:33], v[238:239] op_sel:[0,1]
	v_pk_mul_f32 v[34:35], v[34:35], v[238:239] op_sel:[0,1]
	v_pk_mul_f32 v[36:37], v[36:37], v[238:239] op_sel:[0,1]
	v_pk_mul_f32 v[38:39], v[38:39], v[238:239] op_sel:[0,1]
	v_pk_mul_f32 v[224:225], v[32:33], s[100:101]
	v_pk_mul_f32 v[228:229], v[34:35], s[100:101]
	v_exp_f32_e32 v224, v224
	v_exp_f32_e32 v225, v225
	v_exp_f32_e32 v228, v228
	v_exp_f32_e32 v229, v229
	v_add_f32_e32 v224, 1.0, v224
	v_add_f32_e32 v225, 1.0, v225
	v_add_f32_e32 v228, 1.0, v228
	v_add_f32_e32 v229, 1.0, v229
	v_rcp_f32_e32 v224, v224
; __device__ __forceinline__ unsigned cvt_pk_bf16(float lo, float hi) { unsigned r; asm volatile("v_cvt_pk_bf16_f32 %0, %1, %2" : "=v"(r) : "v"(lo), "v"(hi)); return r; }
; __device__ __forceinline__ float siluf_(float x) { return x * sigmoidf_(x); }
;     __device__ __forceinline__ void operator()(const f32x4 (&acc)[2][2][4][2], const Unit& u, int wr, int wc, int fr, int fq) const {
;     ...
;             for (int m = 0; m < 4; ++m) { const int row = row0 + ai * HALF + m * 16; bf16_t* rowp = O + (size_t)row * ldc + col0; const float rs = rsv[ai][m];
;                 f32x4 v0, v1;
; #pragma unroll
;                 for (int j = 0; j < 4; ++j) { v0[j] = siluf_(acc[ai][0][m][0][j] * rs) * (acc[ai][1][m][0][j] * rs); v1[j] = siluf_(acc[ai][0][m][1][j] * rs) * (acc[ai][1][m][1][j] * rs); }
;                 u32x4 w; w.x = cvt_pk_bf16(v0[0], v0[1]); w.y = cvt_pk_bf16(v0[2], v0[3]); w.z = cvt_pk_bf16(v1[0], v1[1]); w.w = cvt_pk_bf16(v1[2], v1[3]);
;                 *(u32x4*)rowp = w; }
	v_rcp_f32_e32 v225, v225
	v_rcp_f32_e32 v228, v228
	v_rcp_f32_e32 v229, v229
	v_nop
	v_pk_mul_f32 v[32:33], v[32:33], v[224:225]
	v_pk_mul_f32 v[34:35], v[34:35], v[228:229]
	v_pk_mul_f32 v[32:33], v[32:33], v[36:37]
	v_pk_mul_f32 v[34:35], v[34:35], v[38:39]
	v_cvt_pk_bf16_f32 v40, v40, v41
	v_cvt_pk_bf16_f32 v41, v42, v43
	v_cvt_pk_bf16_f32 v42, v32, v33
	v_cvt_pk_bf16_f32 v43, v34, v35
	global_store_dwordx4 v[232:233], v[40:43], off
	v_lshl_add_u64 v[232:233], v[232:233], 0, s[98:99]
	v_pk_mul_f32 v[24:25], v[24:25], v[230:231] op_sel_hi:[1,0]
	v_pk_mul_f32 v[26:27], v[26:27], v[230:231] op_sel_hi:[1,0]
	v_pk_mul_f32 v[28:29], v[28:29], v[230:231] op_sel_hi:[1,0]
	v_pk_mul_f32 v[30:31], v[30:31], v[230:231] op_sel_hi:[1,0]
	v_pk_mul_f32 v[224:225], v[24:25], s[100:101]
	v_pk_mul_f32 v[228:229], v[26:27], s[100:101]
	v_exp_f32_e32 v224, v224
	v_exp_f32_e32 v225, v225
	v_exp_f32_e32 v228, v228
	v_exp_f32_e32 v229, v229
	v_add_f32_e32 v224, 1.0, v224
	v_add_f32_e32 v225, 1.0, v225
	v_add_f32_e32 v228, 1.0, v228
	v_add_f32_e32 v229, 1.0, v229
	v_rcp_f32_e32 v224, v224
	v_rcp_f32_e32 v225, v225
	v_rcp_f32_e32 v228, v228
	v_rcp_f32_e32 v229, v229
	v_nop
	v_pk_mul_f32 v[24:25], v[24:25], v[224:225]
	v_pk_mul_f32 v[26:27], v[26:27], v[228:229]
	v_pk_mul_f32 v[24:25], v[24:25], v[28:29]
	v_pk_mul_f32 v[26:27], v[26:27], v[30:31]
	v_pk_mul_f32 v[16:17], v[16:17], v[230:231] op_sel_hi:[1,0]
	v_pk_mul_f32 v[18:19], v[18:19], v[230:231] op_sel_hi:[1,0]
	v_pk_mul_f32 v[20:21], v[20:21], v[230:231] op_sel_hi:[1,0]
	v_pk_mul_f32 v[22:23], v[22:23], v[230:231] op_sel_hi:[1,0]
	v_pk_mul_f32 v[224:225], v[16:17], s[100:101]
	v_pk_mul_f32 v[228:229], v[18:19], s[100:101]
	v_exp_f32_e32 v224, v224
	v_exp_f32_e32 v225, v225
	v_exp_f32_e32 v228, v228
	v_exp_f32_e32 v229, v229
	v_add_f32_e32 v224, 1.0, v224
	v_add_f32_e32 v225, 1.0, v225
	v_add_f32_e32 v228, 1.0, v228
	v_add_f32_e32 v229, 1.0, v229
	v_rcp_f32_e32 v224, v224
	v_rcp_f32_e32 v225, v225
	v_rcp_f32_e32 v228, v228
	v_rcp_f32_e32 v229, v229
	v_nop
	v_pk_mul_f32 v[16:17], v[16:17], v[224:225]
	v_pk_mul_f32 v[18:19], v[18:19], v[228:229]
	v_pk_mul_f32 v[16:17], v[16:17], v[20:21]
	v_pk_mul_f32 v[18:19], v[18:19], v[22:23]
	v_cvt_pk_bf16_f32 v24, v24, v25
	v_cvt_pk_bf16_f32 v25, v26, v27
	v_cvt_pk_bf16_f32 v26, v16, v17
	v_cvt_pk_bf16_f32 v27, v18, v19
	global_store_dwordx4 v[232:233], v[24:27], off
	v_lshl_add_u64 v[232:233], v[232:233], 0, s[98:99]
	v_pk_mul_f32 v[8:9], v[8:9], v[230:231] op_sel:[0,1]
	v_pk_mul_f32 v[10:11], v[10:11], v[230:231] op_sel:[0,1]
	v_pk_mul_f32 v[12:13], v[12:13], v[230:231] op_sel:[0,1]
	v_pk_mul_f32 v[14:15], v[14:15], v[230:231] op_sel:[0,1]
	v_pk_mul_f32 v[224:225], v[8:9], s[100:101]
	v_pk_mul_f32 v[228:229], v[10:11], s[100:101]
	v_exp_f32_e32 v224, v224
	v_exp_f32_e32 v225, v225
	v_exp_f32_e32 v228, v228
	v_exp_f32_e32 v229, v229
	v_add_f32_e32 v224, 1.0, v224
	v_add_f32_e32 v225, 1.0, v225
	v_add_f32_e32 v228, 1.0, v228
	v_add_f32_e32 v229, 1.0, v229
	v_rcp_f32_e32 v224, v224
	v_rcp_f32_e32 v225, v225
	v_rcp_f32_e32 v228, v228
	v_rcp_f32_e32 v229, v229
	v_nop
	v_pk_mul_f32 v[8:9], v[8:9], v[224:225]
	v_pk_mul_f32 v[10:11], v[10:11], v[228:229]
	v_pk_mul_f32 v[8:9], v[8:9], v[12:13]
	v_pk_mul_f32 v[10:11], v[10:11], v[14:15]
	v_pk_mul_f32 v[4:5], v[4:5], v[230:231] op_sel:[0,1]
	v_pk_mul_f32 v[6:7], v[6:7], v[230:231] op_sel:[0,1]
	v_pk_mul_f32 v[0:1], v[0:1], v[230:231] op_sel:[0,1]
	v_pk_mul_f32 v[2:3], v[2:3], v[230:231] op_sel:[0,1]
	v_pk_mul_f32 v[224:225], v[4:5], s[100:101]
	v_pk_mul_f32 v[228:229], v[6:7], s[100:101]
	v_exp_f32_e32 v224, v224
	v_exp_f32_e32 v225, v225
	v_exp_f32_e32 v228, v228
	v_exp_f32_e32 v229, v229
	v_add_f32_e32 v224, 1.0, v224
	v_add_f32_e32 v225, 1.0, v225
	v_add_f32_e32 v228, 1.0, v228
	v_add_f32_e32 v229, 1.0, v229
	v_rcp_f32_e32 v224, v224
	v_rcp_f32_e32 v225, v225
	v_rcp_f32_e32 v228, v228
	v_rcp_f32_e32 v229, v229
	v_nop
	v_pk_mul_f32 v[4:5], v[4:5], v[224:225]
	v_pk_mul_f32 v[6:7], v[6:7], v[228:229]
	v_pk_mul_f32 v[4:5], v[4:5], v[0:1]
	v_pk_mul_f32 v[6:7], v[6:7], v[2:3]
	v_cvt_pk_bf16_f32 v8, v8, v9
	v_cvt_pk_bf16_f32 v9, v10, v11
	v_cvt_pk_bf16_f32 v10, v4, v5
	v_cvt_pk_bf16_f32 v11, v6, v7
	global_store_dwordx4 v[232:233], v[8:11], off
	s_mov_b32 s101, 0
	s_mov_b64 s[10:11], -1
	s_and_b64 vcc, exec, s[8:9]
	s_cbranch_vccnz .LBB0_299
	s_andn2_b64 vcc, exec, s[40:41]
	s_cbranch_vccnz .LBB0_298
	s_barrier
	s_branch .LBB0_298

; __device__ __forceinline__ void load_rstd(float (&rsv)[2][4], const ssq_t* ssq, int row0) {
;     ssq_t t[2][4];
; #pragma unroll
;     for (int ai = 0; ai < 2; ++ai)
; #pragma unroll
;         for (int m = 0; m < 4; ++m) t[ai][m] = ssq[row0 + ai * HALF + m * 16];
; #pragma unroll
;     for (int ai = 0; ai < 2; ++ai)
; #pragma unroll
;         for (int m = 0; m < 4; ++m) rsv[ai][m] = __builtin_amdgcn_rsqf((float)t[ai][m] * (SSQ_INV / 1024.0f) + 1e-6f);
; }
.LBB0_352:
	s_andn2_b64 vcc, exec, s[36:37]
	s_cbranch_vccnz .LBB0_355
	v_lshl_add_u64 v[142:143], v[142:143], 0, s[92:93]
	v_lshl_add_u64 v[144:145], v[144:145], 0, s[80:81]
	s_mov_b32 s10, 0
	v_readfirstlane_b32 s98, v254
	s_cmp_eq_u32 s98, s61
	s_cbranch_scc1 .Lq5_rs_ok
	s_or_b32 s99, s61, 0x40000000
	s_cmp_eq_u32 s98, s99
	s_cbranch_scc1 .Lq5_rs_wait
	v_lshrrev_b32_e32 v194, 8, v170
	v_and_b32_e32 v195, 15, v170
	v_lshl_add_u32 v194, v194, 6, v195
	s_lshl_b32 s98, s61, 8
	v_add_u32_e32 v194, s98, v194
	v_lshlrev_b32_e32 v192, 3, v194
	v_mov_b32_e32 v193, 0
	v_lshl_add_u64 v[192:193], v[192:193], 0, s[26:27]
	global_load_dwordx2 v[176:177], v[192:193], off
	global_load_dwordx2 v[178:179], v[192:193], off offset:128
	global_load_dwordx2 v[180:181], v[192:193], off offset:256
	global_load_dwordx2 v[182:183], v[192:193], off offset:384
	global_load_dwordx2 v[184:185], v[192:193], off offset:1024
	global_load_dwordx2 v[186:187], v[192:193], off offset:1152
	global_load_dwordx2 v[188:189], v[192:193], off offset:1280
	global_load_dwordx2 v[190:191], v[192:193], off offset:1408
	s_waitcnt vmcnt(0)
	s_branch .Lq5_rs_cvt
.Lq5_rs_wait:
	s_waitcnt vmcnt(8)
.Lq5_rs_cvt:
	v_ffbh_u32_e32 v194, v177
	v_min_u32_e32 v194, 32, v194
	v_lshlrev_b64 v[176:177], v194, v[176:177]
	v_min_u32_e32 v176, 1, v176
	v_or_b32_e32 v176, v177, v176
	v_cvt_f32_u32_e32 v176, v176
	v_sub_u32_e32 v194, 32, v194
	v_ldexp_f32 v176, v176, v194
	v_fmamk_f32 v176, v176, 0x30800000, v223
	v_rsq_f32_e32 v176, v176
	v_ffbh_u32_e32 v194, v179
	v_min_u32_e32 v194, 32, v194
	v_lshlrev_b64 v[178:179], v194, v[178:179]
	v_min_u32_e32 v178, 1, v178
	v_or_b32_e32 v178, v179, v178
	v_cvt_f32_u32_e32 v178, v178
	v_sub_u32_e32 v194, 32, v194
	v_ldexp_f32 v178, v178, v194
	v_fmamk_f32 v178, v178, 0x30800000, v223
	v_rsq_f32_e32 v178, v178
	v_ffbh_u32_e32 v194, v181
	v_min_u32_e32 v194, 32, v194
	v_lshlrev_b64 v[180:181], v194, v[180:181]
	v_min_u32_e32 v180, 1, v180
	v_or_b32_e32 v180, v181, v180
	v_cvt_f32_u32_e32 v180, v180
	v_sub_u32_e32 v194, 32, v194
	v_ldexp_f32 v180, v180, v194
	v_fmamk_f32 v180, v180, 0x30800000, v223
	v_rsq_f32_e32 v180, v180
	v_ffbh_u32_e32 v194, v183
	v_min_u32_e32 v194, 32, v194
	v_lshlrev_b64 v[182:183], v194, v[182:183]
	v_min_u32_e32 v182, 1, v182
	v_or_b32_e32 v182, v183, v182
	v_cvt_f32_u32_e32 v182, v182
	v_sub_u32_e32 v194, 32, v194
	v_ldexp_f32 v182, v182, v194
	v_fmamk_f32 v182, v182, 0x30800000, v223
	v_rsq_f32_e32 v182, v182
	v_ffbh_u32_e32 v194, v185
	v_min_u32_e32 v194, 32, v194
	v_lshlrev_b64 v[184:185], v194, v[184:185]
	v_min_u32_e32 v184, 1, v184
	v_or_b32_e32 v184, v185, v184
	v_cvt_f32_u32_e32 v184, v184
	v_sub_u32_e32 v194, 32, v194
	v_ldexp_f32 v184, v184, v194
	v_fmamk_f32 v184, v184, 0x30800000, v223
	v_rsq_f32_e32 v184, v184
	v_ffbh_u32_e32 v194, v187
	v_min_u32_e32 v194, 32, v194
	v_lshlrev_b64 v[186:187], v194, v[186:187]
	v_min_u32_e32 v186, 1, v186
	v_or_b32_e32 v186, v187, v186
	v_cvt_f32_u32_e32 v186, v186
	v_sub_u32_e32 v194, 32, v194
	v_ldexp_f32 v186, v186, v194
	v_fmamk_f32 v186, v186, 0x30800000, v223
	v_rsq_f32_e32 v186, v186
	v_ffbh_u32_e32 v194, v189
	v_min_u32_e32 v194, 32, v194
	v_lshlrev_b64 v[188:189], v194, v[188:189]
	v_min_u32_e32 v188, 1, v188
	v_or_b32_e32 v188, v189, v188
	v_cvt_f32_u32_e32 v188, v188
	v_sub_u32_e32 v194, 32, v194
	v_ldexp_f32 v188, v188, v194
	v_fmamk_f32 v188, v188, 0x30800000, v223
	v_rsq_f32_e32 v188, v188
	v_ffbh_u32_e32 v194, v191
	v_min_u32_e32 v194, 32, v194
	v_lshlrev_b64 v[190:191], v194, v[190:191]
	v_min_u32_e32 v190, 1, v190
	v_or_b32_e32 v190, v191, v190
	v_cvt_f32_u32_e32 v190, v190
	v_sub_u32_e32 v194, 32, v194
	v_ldexp_f32 v190, v190, v194
	v_fmamk_f32 v190, v190, 0x30800000, v223
	v_rsq_f32_e32 v190, v190
	v_mov_b32_e32 v172, v176
	v_mov_b32_e32 v173, v178
	v_mov_b32_e32 v236, v180
	v_mov_b32_e32 v237, v182
	v_mov_b32_e32 v238, v184
	v_mov_b32_e32 v239, v186
	v_mov_b32_e32 v230, v188
	v_mov_b32_e32 v231, v190
	v_mov_b32_e32 v254, s61

; __device__ __forceinline__ unsigned cvt_pk_bf16(float lo, float hi) { unsigned r; asm volatile("v_cvt_pk_bf16_f32 %0, %1, %2" : "=v"(r) : "v"(lo), "v"(hi)); return r; }
; __device__ __forceinline__ float gelu_tanh(float x) { const float u = 0.7978845608028654f * (x + 0.044715f * x * x * x); return x * fast_rcp(1.0f + fast_exp2(-2.0f * LOG2E * u)); }
; __device__ __forceinline__ void load_rstd(float (&rsv)[2][4], const ssq_t* ssq, int row0) {
;     ssq_t t[2][4];
; #pragma unroll
;     for (int ai = 0; ai < 2; ++ai)
; #pragma unroll
;         for (int m = 0; m < 4; ++m) t[ai][m] = ssq[row0 + ai * HALF + m * 16];
;     __device__ __forceinline__ void operator()(const f32x4 (&acc)[2][2][4][2], const Unit& u, int wr, int wc, int fr, int fq) const {
;         const int row0 = u.pm * BM + wr * 64 + fr, col0 = u.pn * BM + wc * 32 + 8 * fq;
;         float rsv[2][4]; load_rstd(rsv, ssq, row0);
; #pragma unroll
;         for (int ai = 0; ai < 2; ++ai)
; #pragma unroll
;             for (int m = 0; m < 4; ++m) { const int row = row0 + ai * HALF + m * 16; bf16_t* rowp = O + (size_t)row * ldc + col0; const float rs = rsv[ai][m];
; #pragma unroll
;                 for (int bj = 0; bj < 2; ++bj) { f32x4 v0 = acc[ai][bj][m][0] * rs, v1 = acc[ai][bj][m][1] * rs;
;                     if (ACT == 1) {
; #pragma unroll
;                         for (int j = 0; j < 4; ++j) { v0[j] = gelu_tanh(v0[j]); v1[j] = gelu_tanh(v1[j]); } }
;                     u32x4 w; w.x = cvt_pk_bf16(v0[0], v0[1]); w.y = cvt_pk_bf16(v0[2], v0[3]); w.z = cvt_pk_bf16(v1[0], v1[1]); w.w = cvt_pk_bf16(v1[2], v1[3]);
;                     *(u32x4*)(rowp + bj * HALF) = w; } }
.LBB0_357:
	s_nop 15
	s_nop 15
	s_and_b64 vcc, exec, s[8:9]
	s_cbranch_vccnz .Lq5_nopf
	s_cmp_eq_u32 s59, s61
	s_cbranch_scc1 .Lq5_nopf
	v_lshrrev_b32_e32 v194, 8, v170
	v_and_b32_e32 v195, 15, v170
	v_lshl_add_u32 v194, v194, 6, v195
	s_lshl_b32 s98, s59, 8
	v_add_u32_e32 v194, s98, v194
	v_lshlrev_b32_e32 v192, 3, v194
	v_mov_b32_e32 v193, 0
	v_lshl_add_u64 v[192:193], v[192:193], 0, s[26:27]
	global_load_dwordx2 v[176:177], v[192:193], off
	global_load_dwordx2 v[178:179], v[192:193], off offset:128
	global_load_dwordx2 v[180:181], v[192:193], off offset:256
	global_load_dwordx2 v[182:183], v[192:193], off offset:384
	global_load_dwordx2 v[184:185], v[192:193], off offset:1024
	global_load_dwordx2 v[186:187], v[192:193], off offset:1152
	global_load_dwordx2 v[188:189], v[192:193], off offset:1280
	global_load_dwordx2 v[190:191], v[192:193], off offset:1408
	s_or_b32 s98, s59, 0x40000000
	v_mov_b32_e32 v254, s98
.Lq5_nopf:
	s_lshl_b32 s98, s28, 5
	s_mov_b32 s99, 0
	v_pk_mul_f32 v[60:61], v[60:61], v[238:239] op_sel_hi:[1,0]
	v_pk_mul_f32 v[62:63], v[62:63], v[238:239] op_sel_hi:[1,0]
	v_pk_mul_f32 v[56:57], v[56:57], v[238:239] op_sel_hi:[1,0]
	v_pk_mul_f32 v[58:59], v[58:59], v[238:239] op_sel_hi:[1,0]
	v_cvt_pk_bf16_f32 v60, v60, v61
	v_cvt_pk_bf16_f32 v61, v62, v63
	v_cvt_pk_bf16_f32 v62, v56, v57
	v_cvt_pk_bf16_f32 v63, v58, v59
	global_store_dwordx4 v[232:233], v[60:63], off
	v_pk_mul_f32 v[52:53], v[52:53], v[238:239] op_sel_hi:[1,0]
	v_pk_mul_f32 v[54:55], v[54:55], v[238:239] op_sel_hi:[1,0]
	v_pk_mul_f32 v[48:49], v[48:49], v[238:239] op_sel_hi:[1,0]
	v_pk_mul_f32 v[50:51], v[50:51], v[238:239] op_sel_hi:[1,0]
	v_cvt_pk_bf16_f32 v52, v52, v53
	v_cvt_pk_bf16_f32 v53, v54, v55
	v_cvt_pk_bf16_f32 v54, v48, v49
	v_cvt_pk_bf16_f32 v55, v50, v51
	global_store_dwordx4 v[232:233], v[52:55], off offset:256
	v_lshl_add_u64 v[232:233], v[232:233], 0, s[98:99]
	v_pk_mul_f32 v[44:45], v[44:45], v[238:239] op_sel:[0,1]
	v_pk_mul_f32 v[46:47], v[46:47], v[238:239] op_sel:[0,1]
	v_pk_mul_f32 v[40:41], v[40:41], v[238:239] op_sel:[0,1]
	v_pk_mul_f32 v[42:43], v[42:43], v[238:239] op_sel:[0,1]
	v_cvt_pk_bf16_f32 v44, v44, v45
	v_cvt_pk_bf16_f32 v45, v46, v47
	v_cvt_pk_bf16_f32 v46, v40, v41
	v_cvt_pk_bf16_f32 v47, v42, v43
	global_store_dwordx4 v[232:233], v[44:47], off
	v_pk_mul_f32 v[36:37], v[36:37], v[238:239] op_sel:[0,1]
	v_pk_mul_f32 v[38:39], v[38:39], v[238:239] op_sel:[0,1]
	v_pk_mul_f32 v[32:33], v[32:33], v[238:239] op_sel:[0,1]
	v_pk_mul_f32 v[34:35], v[34:35], v[238:239] op_sel:[0,1]
	v_cvt_pk_bf16_f32 v36, v36, v37
	v_cvt_pk_bf16_f32 v37, v38, v39
	v_cvt_pk_bf16_f32 v38, v32, v33
	v_cvt_pk_bf16_f32 v39, v34, v35
	global_store_dwordx4 v[232:233], v[36:39], off offset:256
	v_lshl_add_u64 v[232:233], v[232:233], 0, s[98:99]
	v_pk_mul_f32 v[28:29], v[28:29], v[230:231] op_sel_hi:[1,0]
	v_pk_mul_f32 v[30:31], v[30:31], v[230:231] op_sel_hi:[1,0]
	v_pk_mul_f32 v[24:25], v[24:25], v[230:231] op_sel_hi:[1,0]
	v_pk_mul_f32 v[26:27], v[26:27], v[230:231] op_sel_hi:[1,0]
	v_cvt_pk_bf16_f32 v28, v28, v29
	v_cvt_pk_bf16_f32 v29, v30, v31
	v_cvt_pk_bf16_f32 v30, v24, v25
	v_cvt_pk_bf16_f32 v31, v26, v27
	global_store_dwordx4 v[232:233], v[28:31], off
	v_pk_mul_f32 v[20:21], v[20:21], v[230:231] op_sel_hi:[1,0]
	v_pk_mul_f32 v[22:23], v[22:23], v[230:231] op_sel_hi:[1,0]
	v_pk_mul_f32 v[16:17], v[16:17], v[230:231] op_sel_hi:[1,0]
	v_pk_mul_f32 v[18:19], v[18:19], v[230:231] op_sel_hi:[1,0]
	v_cvt_pk_bf16_f32 v20, v20, v21
	v_cvt_pk_bf16_f32 v21, v22, v23
	v_cvt_pk_bf16_f32 v22, v16, v17
	v_cvt_pk_bf16_f32 v23, v18, v19
	global_store_dwordx4 v[232:233], v[20:23], off offset:256
	v_lshl_add_u64 v[232:233], v[232:233], 0, s[98:99]
	v_pk_mul_f32 v[12:13], v[12:13], v[230:231] op_sel:[0,1]
	v_pk_mul_f32 v[14:15], v[14:15], v[230:231] op_sel:[0,1]
	v_pk_mul_f32 v[8:9], v[8:9], v[230:231] op_sel:[0,1]
	v_pk_mul_f32 v[10:11], v[10:11], v[230:231] op_sel:[0,1]
	v_cvt_pk_bf16_f32 v12, v12, v13
	v_cvt_pk_bf16_f32 v13, v14, v15
	v_cvt_pk_bf16_f32 v14, v8, v9
	v_cvt_pk_bf16_f32 v15, v10, v11
	global_store_dwordx4 v[232:233], v[12:15], off
	v_pk_mul_f32 v[4:5], v[4:5], v[230:231] op_sel:[0,1]
	v_pk_mul_f32 v[6:7], v[6:7], v[230:231] op_sel:[0,1]
	v_pk_mul_f32 v[0:1], v[0:1], v[230:231] op_sel:[0,1]
	v_pk_mul_f32 v[2:3], v[2:3], v[230:231] op_sel:[0,1]
	v_cvt_pk_bf16_f32 v4, v4, v5
	v_cvt_pk_bf16_f32 v5, v6, v7
	v_cvt_pk_bf16_f32 v6, v0, v1
	v_cvt_pk_bf16_f32 v7, v2, v3
	global_store_dwordx4 v[232:233], v[4:7], off offset:256
	s_mov_b32 s101, 0
	s_mov_b64 s[10:11], -1
	s_and_b64 vcc, exec, s[8:9]
	s_cbranch_vccnz .LBB0_345
	s_andn2_b64 vcc, exec, s[40:41]
	s_cbranch_vccnz .LBB0_344
	s_barrier
	s_branch .LBB0_344
